# SWA+mem attention: PV V-fragment LDS reads prefetched into free VGPRs with counted waits (on top of SWA bias de-serialisation)
# baseline (speedup 1.0000x reference)
.LBB0_1446:
	s_or_b64 exec, exec, s[6:7]
	v_add_u32_e32 v64, 0xffffff81, v101
	v_cmp_gt_u32_e32 vcc, s91, v64
	s_waitcnt lgkmcnt(1)
	v_add_f32_e32 v48, v48, v63
	v_add_u32_e32 v63, 0xffffff82, v101
	v_cndmask_b32_e32 v48, v213, v48, vcc
	v_cmp_gt_u32_e32 vcc, s91, v63
	v_add_f32_e32 v47, v47, v137
	v_add_u32_e32 v63, 0xffffff83, v101
	v_cndmask_b32_e32 v47, v213, v47, vcc
	v_cmp_gt_u32_e32 vcc, s91, v63
	v_add_f32_e32 v46, v46, v136
	v_add_u32_e32 v63, 0xffffff88, v101
	v_cndmask_b32_e32 v46, v213, v46, vcc
	v_cmp_gt_u32_e32 vcc, s91, v63
	v_add_f32_e32 v45, v45, v135
	v_add_f32_e32 v44, v44, v134
	v_cndmask_b32_e32 v63, v213, v45, vcc
	v_add_u32_e32 v45, 0xffffff89, v101
	v_cmp_gt_u32_e32 vcc, s91, v45
	v_add_f32_e32 v43, v43, v133
	v_add_f32_e32 v42, v42, v132
	v_cndmask_b32_e32 v134, v213, v44, vcc
	v_add_u32_e32 v44, 0xffffff8a, v101
	v_cmp_gt_u32_e32 vcc, s91, v44
	v_add_f32_e32 v41, v41, v131
	v_add_f32_e32 v40, v40, v130
	v_cndmask_b32_e32 v133, v213, v43, vcc
	v_add_u32_e32 v43, 0xffffff8b, v101
	v_cmp_gt_u32_e32 vcc, s91, v43
	v_add_f32_e32 v39, v39, v129
	v_add_f32_e32 v38, v38, v128
	v_cndmask_b32_e32 v64, v213, v42, vcc
	v_add_u32_e32 v42, 0xffffff90, v101
	v_cmp_gt_u32_e32 vcc, s91, v42
	v_add_u32_e32 v42, 0xffffff91, v101
	v_add_f32_e32 v37, v37, v127
	v_cndmask_b32_e32 v41, v213, v41, vcc
	v_cmp_gt_u32_e32 vcc, s91, v42
	v_add_f32_e32 v36, v36, v51
	v_add_f32_e32 v35, v35, v126
	v_cndmask_b32_e32 v44, v213, v40, vcc
	v_add_u32_e32 v40, 0xffffff92, v101
	v_cmp_gt_u32_e32 vcc, s91, v40
	v_add_f32_e32 v34, v34, v125
	s_nop 0
	v_cndmask_b32_e32 v45, v213, v39, vcc
	v_add_u32_e32 v39, 0xffffff93, v101
	v_cmp_gt_u32_e32 vcc, s91, v39
	v_max_f32_e32 v39, v50, v50
	s_nop 0
	v_cndmask_b32_e32 v42, v213, v38, vcc
	v_add_u32_e32 v38, 0xffffff98, v101
	v_cmp_gt_u32_e32 vcc, s91, v38
	s_nop 1
	v_cndmask_b32_e32 v40, v213, v37, vcc
	v_add_u32_e32 v37, 0xffffff99, v101
	v_cmp_gt_u32_e32 vcc, s91, v37
	v_max_f32_e32 v37, v122, v122
	v_max_f32_e32 v39, v39, v40
	v_cndmask_b32_e32 v38, v213, v36, vcc
	v_add_u32_e32 v36, 0xffffff9a, v101
	v_cmp_gt_u32_e32 vcc, s91, v36
	v_add_u32_e32 v36, 0xffffff9b, v101
	v_max_f32_e32 v37, v37, v38
	v_cndmask_b32_e32 v35, v213, v35, vcc
	v_cmp_gt_u32_e32 vcc, s91, v36
	v_add_u32_e32 v36, 0xffffff80, v101
	s_nop 0
	v_cndmask_b32_e32 v34, v213, v34, vcc
	v_cmp_gt_u32_e32 vcc, s91, v36
	s_waitcnt lgkmcnt(0)
	v_add_f32_e32 v36, v49, v62
	v_cndmask_b32_e32 v49, v213, v36, vcc
	v_max_f32_e32 v36, v120, v120
	v_max_f32_e32 v36, v36, v35
	v_max3_f32 v36, v121, v34, v36
	v_max3_f32 v36, v36, v37, v39
	v_max_f32_e32 v37, v123, v123
	v_max_f32_e32 v39, v52, v52
	v_max_f32_e32 v37, v37, v42
	v_max_f32_e32 v39, v39, v45
	v_max3_f32 v36, v36, v37, v39
	v_max_f32_e32 v37, v124, v124
	v_max_f32_e32 v39, v53, v53
	v_max_f32_e32 v37, v37, v44
	v_max_f32_e32 v39, v39, v41
	v_max3_f32 v36, v36, v37, v39
	v_max_f32_e32 v37, v57, v57
	v_max_f32_e32 v39, v54, v54
	v_max_f32_e32 v37, v37, v64
	v_max_f32_e32 v39, v39, v133
	v_max3_f32 v36, v36, v37, v39
	v_max_f32_e32 v37, v59, v59
	v_max_f32_e32 v39, v55, v55
	v_max_f32_e32 v37, v37, v134
	v_max_f32_e32 v39, v39, v63
	v_max3_f32 v36, v36, v37, v39
	v_max_f32_e32 v37, v60, v60
	v_max_f32_e32 v39, v56, v56
	v_max_f32_e32 v37, v37, v46
	v_max_f32_e32 v39, v39, v47
	v_max3_f32 v36, v36, v37, v39
	v_max_f32_e32 v37, v61, v61
	v_max_f32_e32 v39, v58, v58
	v_max_f32_e32 v37, v37, v48
	v_max_f32_e32 v39, v39, v49
	v_max3_f32 v36, v36, v37, v39
	ds_bpermute_b32 v37, v111, v36
	s_waitcnt lgkmcnt(0)
	v_max3_f32 v51, v119, v36, v37
	v_sub_f32_e32 v34, v34, v51
	v_sub_f32_e32 v36, v121, v51
	v_exp_f32_e32 v127, v34
	v_sub_f32_e32 v34, v120, v51
	v_exp_f32_e32 v126, v36
	v_exp_f32_e32 v36, v34
	v_sub_f32_e32 v34, v35, v51
	v_sub_f32_e32 v35, v122, v51
	v_exp_f32_e32 v128, v35
	v_sub_f32_e32 v35, v38, v51
	v_exp_f32_e32 v129, v35
	v_sub_f32_e32 v35, v50, v51
	v_exp_f32_e32 v38, v35
	v_sub_f32_e32 v35, v40, v51
	v_exp_f32_e32 v40, v35
	v_sub_f32_e32 v35, v123, v51
	v_exp_f32_e32 v130, v35
	v_sub_f32_e32 v35, v42, v51
	v_exp_f32_e32 v131, v35
	v_sub_f32_e32 v35, v52, v51
	v_exp_f32_e32 v42, v35
	v_sub_f32_e32 v35, v45, v51
	v_exp_f32_e32 v52, v35
	v_sub_f32_e32 v35, v124, v51
	v_exp_f32_e32 v132, v35
	v_sub_f32_e32 v35, v44, v51
	v_exp_f32_e32 v135, v35
	v_sub_f32_e32 v35, v53, v51
	v_exp_f32_e32 v44, v35
	v_sub_f32_e32 v35, v41, v51
	v_exp_f32_e32 v62, v35
	v_sub_f32_e32 v35, v57, v51
	v_exp_f32_e32 v136, v35
	v_sub_f32_e32 v35, v64, v51
	v_exp_f32_e32 v137, v35
	v_sub_f32_e32 v35, v54, v51
	v_exp_f32_e32 v64, v35
	v_sub_f32_e32 v35, v133, v51
	v_exp_f32_e32 v54, v35
	v_sub_f32_e32 v35, v59, v51
	v_exp_f32_e32 v133, v35
	v_sub_f32_e32 v35, v134, v51
	v_exp_f32_e32 v134, v35
	v_sub_f32_e32 v35, v55, v51
	v_exp_f32_e32 v120, v35
	v_sub_f32_e32 v35, v63, v51
	v_exp_f32_e32 v122, v35
	v_sub_f32_e32 v35, v60, v51
	v_exp_f32_e32 v138, v35
	v_sub_f32_e32 v35, v46, v51
	v_exp_f32_e32 v139, v35
	v_sub_f32_e32 v35, v56, v51
	v_exp_f32_e32 v56, v35
	v_sub_f32_e32 v35, v47, v51
	v_exp_f32_e32 v60, v35
	v_sub_f32_e32 v35, v61, v51
	v_exp_f32_e32 v34, v34
	v_exp_f32_e32 v140, v35
	v_sub_f32_e32 v35, v48, v51
	v_exp_f32_e32 v141, v35
	v_sub_f32_e32 v35, v58, v51
	v_exp_f32_e32 v58, v35
	v_sub_f32_e32 v35, v49, v51
	v_add_f32_e32 v37, v126, v127
	v_exp_f32_e32 v124, v35
	v_mov_b32_e32 v35, v0
	v_pk_add_f32 v[46:47], v[36:37], v[34:35]
	v_add_f32_e32 v39, v128, v129
	v_pk_add_f32 v[46:47], v[46:47], v[46:47] op_sel_hi:[0,1]
	v_mov_b32_e32 v41, v47
	v_pk_add_f32 v[46:47], v[38:39], v[40:41]
	v_add_f32_e32 v43, v130, v131
	v_pk_add_f32 v[46:47], v[46:47], v[46:47] op_sel_hi:[0,1]
	v_mov_b32_e32 v53, v47
	v_pk_add_f32 v[46:47], v[42:43], v[52:53]
	v_add_f32_e32 v45, v132, v135
	v_pk_add_f32 v[46:47], v[46:47], v[46:47] op_sel_hi:[0,1]
	v_mov_b32_e32 v63, v47
	v_pk_add_f32 v[46:47], v[44:45], v[62:63]
	v_add_f32_e32 v65, v136, v137
	v_pk_add_f32 v[46:47], v[46:47], v[46:47] op_sel_hi:[0,1]
	v_mov_b32_e32 v55, v47
	v_pk_add_f32 v[46:47], v[64:65], v[54:55]
	v_add_f32_e32 v121, v133, v134
	v_pk_add_f32 v[46:47], v[46:47], v[46:47] op_sel_hi:[0,1]
	v_mov_b32_e32 v123, v47
	v_pk_add_f32 v[46:47], v[120:121], v[122:123]
	v_add_f32_e32 v57, v138, v139
	v_pk_add_f32 v[46:47], v[46:47], v[46:47] op_sel_hi:[0,1]
	v_mov_b32_e32 v61, v47
	v_pk_add_f32 v[46:47], v[56:57], v[60:61]
	v_sub_f32_e32 v119, v119, v51
	v_pk_add_f32 v[46:47], v[46:47], v[46:47] op_sel_hi:[0,1]
	v_add_f32_e32 v59, v140, v141
	v_mov_b32_e32 v125, v47
	v_exp_f32_e32 v50, v119
	v_pk_add_f32 v[46:47], v[58:59], v[124:125]
	v_cvt_pk_bf16_f32 v49, v132, v44
	v_add_f32_e32 v53, v46, v47
	v_cvt_pk_bf16_f32 v46, v126, v36
	v_cvt_pk_bf16_f32 v47, v128, v38
	v_cvt_pk_bf16_f32 v44, v138, v56
	v_cvt_pk_bf16_f32 v45, v140, v58
	v_cvt_pk_bf16_f32 v38, v127, v34
	v_cvt_pk_bf16_f32 v34, v137, v54
	v_cvt_pk_bf16_f32 v36, v139, v60
	ds_read_b128 v[158:161], v118 offset:18432
	ds_read_b128 v[162:165], v118 offset:18464
	ds_read_b128 v[166:169], v118 offset:18496
	ds_read_b128 v[170:173], v118 offset:18528
	ds_read_b128 v[174:177], v118 offset:23040
	ds_read_b128 v[178:181], v118 offset:23072
	ds_read_b128 v[182:185], v118 offset:23104
	ds_read_b128 v[186:189], v118 offset:23136
	v_pk_mul_f32 v[18:19], v[18:19], v[50:51] op_sel_hi:[1,0]
	v_pk_mul_f32 v[20:21], v[20:21], v[50:51] op_sel_hi:[1,0]
	v_pk_mul_f32 v[22:23], v[22:23], v[50:51] op_sel_hi:[1,0]
	v_pk_mul_f32 v[24:25], v[24:25], v[50:51] op_sel_hi:[1,0]
	v_pk_mul_f32 v[26:27], v[26:27], v[50:51] op_sel_hi:[1,0]
	v_pk_mul_f32 v[28:29], v[28:29], v[50:51] op_sel_hi:[1,0]
	v_pk_mul_f32 v[30:31], v[30:31], v[50:51] op_sel_hi:[1,0]
	v_pk_mul_f32 v[32:33], v[32:33], v[50:51] op_sel_hi:[1,0]
	v_cvt_pk_bf16_f32 v48, v130, v42
	v_cvt_pk_bf16_f32 v42, v136, v64
	v_cvt_pk_bf16_f32 v43, v133, v120
	s_waitcnt lgkmcnt(7)
	v_mfma_f32_32x32x16_bf16 v[18:33], v[158:161], v[46:49], v[18:33]
	v_cvt_pk_bf16_f32 v39, v129, v40
	v_cvt_pk_bf16_f32 v40, v131, v52
	v_cvt_pk_bf16_f32 v41, v135, v62
	v_cvt_pk_bf16_f32 v35, v134, v122
	v_cvt_pk_bf16_f32 v37, v141, v124
	v_pk_mul_f32 v[2:3], v[2:3], v[50:51] op_sel_hi:[1,0]
	s_waitcnt lgkmcnt(6)
	v_mfma_f32_32x32x16_bf16 v[18:33], v[162:165], v[42:45], v[18:33]
	v_mul_f32_e64 v4, v4, v50
	v_mul_f32_e64 v5, v5, v50
	v_mul_f32_e64 v6, v6, v50
	v_mul_f32_e64 v7, v7, v50
	v_mul_f32_e64 v8, v8, v50
	v_mul_f32_e64 v9, v9, v50
	v_pk_mul_f32 v[10:11], v[10:11], v[50:51] op_sel_hi:[1,0]
	v_pk_mul_f32 v[12:13], v[12:13], v[50:51] op_sel_hi:[1,0]
	v_pk_mul_f32 v[14:15], v[14:15], v[50:51] op_sel_hi:[1,0]
	v_pk_mul_f32 v[16:17], v[16:17], v[50:51] op_sel_hi:[1,0]
	s_waitcnt lgkmcnt(5)
	v_mfma_f32_32x32x16_bf16 v[18:33], v[166:169], v[38:41], v[18:33]
	v_fmac_f32_e32 v53, v117, v50
	v_mov_b32_e32 v119, v51
	v_mov_b32_e32 v117, v53
	s_waitcnt lgkmcnt(4)
	v_mfma_f32_32x32x16_bf16 v[18:33], v[170:173], v[34:37], v[18:33]
	s_waitcnt lgkmcnt(3)
	v_mfma_f32_32x32x16_bf16 v[2:17], v[174:177], v[46:49], v[2:17]
	s_waitcnt lgkmcnt(2)
	v_mfma_f32_32x32x16_bf16 v[2:17], v[178:181], v[42:45], v[2:17]
	s_waitcnt lgkmcnt(1)
	v_mfma_f32_32x32x16_bf16 v[2:17], v[182:185], v[38:41], v[2:17]
	s_waitcnt lgkmcnt(0)
	v_mfma_f32_32x32x16_bf16 v[2:17], v[186:189], v[34:37], v[2:17]

.LBB0_1470:
	s_and_b32 s4, s16, 1
	s_mul_i32 s5, s4, 0x4400
	v_add_u32_e32 v163, s5, v181
	ds_read_b128 v[66:69], v163 offset:8704
	ds_read_b128 v[70:73], v163
	ds_read_b128 v[186:189], v163 offset:32
	ds_read_b128 v[190:193], v163 offset:8736
	s_mul_i32 s5, s4, 0x4800
	v_add_u32_e32 v201, s5, v183
	s_waitcnt lgkmcnt(2)
	v_mfma_f32_32x32x16_bf16 v[82:97], v[70:73], v[98:101], 0
	s_andn2_b64 vcc, exec, s[2:3]
	v_mfma_f32_32x32x16_bf16 v[66:81], v[66:69], v[98:101], 0
	s_waitcnt lgkmcnt(1)
	v_mfma_f32_32x32x16_bf16 v[82:97], v[186:189], v[102:105], v[82:97]
	s_waitcnt lgkmcnt(0)
	v_mfma_f32_32x32x16_bf16 v[66:81], v[190:193], v[102:105], v[66:81]
	ds_read_b128 v[186:189], v163 offset:64
	ds_read_b128 v[190:193], v163 offset:8768
	s_waitcnt lgkmcnt(1)
	v_mfma_f32_32x32x16_bf16 v[82:97], v[186:189], v[106:109], v[82:97]
	s_waitcnt lgkmcnt(0)
	v_mfma_f32_32x32x16_bf16 v[66:81], v[190:193], v[106:109], v[66:81]
	ds_read_b128 v[186:189], v163 offset:96
	ds_read_b128 v[190:193], v163 offset:8800
	s_waitcnt lgkmcnt(1)
	v_mfma_f32_32x32x16_bf16 v[82:97], v[186:189], v[110:113], v[82:97]
	s_waitcnt lgkmcnt(0)
	v_mfma_f32_32x32x16_bf16 v[66:81], v[190:193], v[110:113], v[66:81]
	ds_read_b128 v[186:189], v163 offset:128
	ds_read_b128 v[190:193], v163 offset:8832
	s_waitcnt lgkmcnt(1)
	v_mfma_f32_32x32x16_bf16 v[82:97], v[186:189], v[114:117], v[82:97]
	s_waitcnt lgkmcnt(0)
	v_mfma_f32_32x32x16_bf16 v[66:81], v[190:193], v[114:117], v[66:81]
	ds_read_b128 v[186:189], v163 offset:160
	ds_read_b128 v[190:193], v163 offset:8864
	s_waitcnt lgkmcnt(1)
	v_mfma_f32_32x32x16_bf16 v[82:97], v[186:189], v[118:121], v[82:97]
	s_waitcnt lgkmcnt(0)
	v_mfma_f32_32x32x16_bf16 v[66:81], v[190:193], v[118:121], v[66:81]
	ds_read_b128 v[186:189], v163 offset:192
	ds_read_b128 v[190:193], v163 offset:8896
	s_waitcnt lgkmcnt(1)
	v_mfma_f32_32x32x16_bf16 v[82:97], v[186:189], v[122:125], v[82:97]
	s_waitcnt lgkmcnt(0)
	v_mfma_f32_32x32x16_bf16 v[66:81], v[190:193], v[122:125], v[66:81]
	ds_read_b128 v[186:189], v163 offset:224
	ds_read_b128 v[190:193], v163 offset:8928
	ds_read_b128 v[204:207], v201 offset:34816
	ds_read_b128 v[214:217], v201 offset:34848
	s_waitcnt lgkmcnt(3)
	v_mfma_f32_32x32x16_bf16 v[82:97], v[186:189], v[126:129], v[82:97]
	s_waitcnt lgkmcnt(2)
	v_mfma_f32_32x32x16_bf16 v[66:81], v[190:193], v[126:129], v[66:81]
	s_nop 9
	v_max_f32_e32 v174, v83, v83
	v_max_f32_e32 v186, v84, v84
	v_max_f32_e32 v187, v85, v85
	v_max_f32_e32 v163, v67, v67
	v_max_f32_e32 v163, v174, v163
	v_max_f32_e32 v174, v68, v68
	v_max_f32_e32 v174, v186, v174
	v_max_f32_e32 v186, v69, v69
	v_max3_f32 v163, v82, v66, v163
	v_max_f32_e32 v186, v187, v186
	v_max3_f32 v163, v163, v174, v186
	v_max_f32_e32 v174, v70, v70
	v_max_f32_e32 v186, v86, v86
	v_max_f32_e32 v174, v186, v174
	v_max_f32_e32 v186, v71, v71
	v_max_f32_e32 v187, v87, v87
	v_max_f32_e32 v186, v187, v186
	v_max3_f32 v163, v163, v174, v186
	v_max_f32_e32 v174, v72, v72
	v_max_f32_e32 v186, v88, v88
	v_max_f32_e32 v174, v186, v174
	v_max_f32_e32 v186, v73, v73
	v_max_f32_e32 v187, v89, v89
	v_max_f32_e32 v186, v187, v186
	v_max3_f32 v163, v163, v174, v186
	v_max_f32_e32 v174, v74, v74
	v_max_f32_e32 v186, v90, v90
	v_max_f32_e32 v174, v186, v174
	v_max_f32_e32 v186, v75, v75
	v_max_f32_e32 v187, v91, v91
	v_max_f32_e32 v186, v187, v186
	v_max3_f32 v163, v163, v174, v186
	v_max_f32_e32 v174, v76, v76
	v_max_f32_e32 v186, v92, v92
	v_max_f32_e32 v174, v186, v174
	v_max_f32_e32 v186, v77, v77
	v_max_f32_e32 v187, v93, v93
	v_max_f32_e32 v186, v187, v186
	v_max3_f32 v163, v163, v174, v186
	v_max_f32_e32 v174, v78, v78
	v_max_f32_e32 v186, v94, v94
	v_max_f32_e32 v174, v186, v174
	v_max_f32_e32 v186, v79, v79
	v_max_f32_e32 v187, v95, v95
	v_max_f32_e32 v186, v187, v186
	v_max3_f32 v163, v163, v174, v186
	v_max_f32_e32 v174, v80, v80
	v_max_f32_e32 v186, v96, v96
	v_max_f32_e32 v174, v186, v174
	v_max_f32_e32 v186, v81, v81
	v_max_f32_e32 v187, v97, v97
	v_max_f32_e32 v186, v187, v186
	v_max3_f32 v163, v163, v174, v186
	ds_bpermute_b32 v174, v182, v163
	s_waitcnt lgkmcnt(0)
	v_max3_f32 v163, v165, v163, v174
	v_sub_f32_e32 v165, v165, v163
	v_sub_f32_e32 v66, v66, v163
	v_exp_f32_e32 v174, v165
	v_exp_f32_e32 v165, v66
	v_sub_f32_e32 v66, v83, v163
	v_exp_f32_e32 v83, v66
	v_sub_f32_e32 v66, v67, v163
	v_exp_f32_e32 v186, v66
	v_sub_f32_e32 v66, v84, v163
	v_exp_f32_e32 v84, v66
	v_sub_f32_e32 v66, v68, v163
	v_exp_f32_e32 v187, v66
	v_sub_f32_e32 v66, v85, v163
	v_exp_f32_e32 v85, v66
	v_sub_f32_e32 v66, v69, v163
	v_exp_f32_e32 v188, v66
	v_sub_f32_e32 v66, v86, v163
	v_exp_f32_e32 v86, v66
	v_sub_f32_e32 v66, v70, v163
	v_exp_f32_e32 v189, v66
	v_sub_f32_e32 v66, v87, v163
	v_exp_f32_e32 v87, v66
	v_sub_f32_e32 v66, v71, v163
	v_exp_f32_e32 v190, v66
	v_sub_f32_e32 v66, v88, v163
	v_exp_f32_e32 v88, v66
	v_sub_f32_e32 v66, v72, v163
	v_exp_f32_e32 v191, v66
	v_sub_f32_e32 v66, v89, v163
	v_exp_f32_e32 v89, v66
	v_sub_f32_e32 v66, v73, v163
	v_exp_f32_e32 v192, v66
	v_sub_f32_e32 v66, v90, v163
	v_exp_f32_e32 v90, v66
	v_sub_f32_e32 v66, v74, v163
	v_exp_f32_e32 v193, v66
	v_sub_f32_e32 v66, v91, v163
	v_exp_f32_e32 v91, v66
	v_sub_f32_e32 v66, v75, v163
	v_exp_f32_e32 v194, v66
	v_sub_f32_e32 v66, v92, v163
	v_exp_f32_e32 v92, v66
	v_sub_f32_e32 v66, v76, v163
	v_exp_f32_e32 v195, v66
	v_sub_f32_e32 v66, v93, v163
	v_exp_f32_e32 v93, v66
	v_sub_f32_e32 v66, v77, v163
	v_exp_f32_e32 v196, v66
	v_sub_f32_e32 v66, v94, v163
	v_exp_f32_e32 v94, v66
	v_sub_f32_e32 v66, v78, v163
	v_sub_f32_e32 v82, v82, v163
	v_exp_f32_e32 v197, v66
	v_sub_f32_e32 v66, v95, v163
	v_exp_f32_e32 v82, v82
	v_exp_f32_e32 v95, v66
	v_sub_f32_e32 v66, v79, v163
	v_exp_f32_e32 v198, v66
	v_sub_f32_e32 v66, v96, v163
	v_exp_f32_e32 v96, v66
	v_sub_f32_e32 v66, v80, v163
	v_exp_f32_e32 v199, v66
	v_sub_f32_e32 v66, v97, v163
	v_exp_f32_e32 v97, v66
	v_sub_f32_e32 v66, v81, v163
	v_pk_mul_f32 v[64:65], v[64:65], v[174:175] op_sel_hi:[1,0]
	v_pk_mul_f32 v[62:63], v[62:63], v[174:175] op_sel_hi:[1,0]
	v_pk_mul_f32 v[60:61], v[60:61], v[174:175] op_sel_hi:[1,0]
	v_pk_mul_f32 v[58:59], v[58:59], v[174:175] op_sel_hi:[1,0]
	v_pk_mul_f32 v[56:57], v[56:57], v[174:175] op_sel_hi:[1,0]
	v_pk_mul_f32 v[54:55], v[54:55], v[174:175] op_sel_hi:[1,0]
	v_pk_mul_f32 v[52:53], v[52:53], v[174:175] op_sel_hi:[1,0]
	v_pk_mul_f32 v[50:51], v[50:51], v[174:175] op_sel_hi:[1,0]
	v_cvt_pk_bf16_f32 v78, v82, v83
	v_cvt_pk_bf16_f32 v79, v84, v85
	v_cvt_pk_bf16_f32 v80, v86, v87
	v_cvt_pk_bf16_f32 v81, v88, v89
	v_cvt_pk_bf16_f32 v70, v90, v91
	v_cvt_pk_bf16_f32 v71, v92, v93
	ds_read_b128 v[218:221], v201 offset:34880
	ds_read_b128 v[222:225], v201 offset:34912
	ds_read_b128 v[226:229], v201 offset:39424
	ds_read_b128 v[230:233], v201 offset:39456
	ds_read_b128 v[234:237], v201 offset:39488
	ds_read_b128 v[238:241], v201 offset:39520
	s_waitcnt lgkmcnt(7)
	v_mfma_f32_32x32x16_bf16 v[50:65], v[204:207], v[78:81], v[50:65]
	ds_read_b128 v[204:207], v201 offset:44032
	v_cvt_pk_bf16_f32 v72, v94, v95
	v_cvt_pk_bf16_f32 v73, v96, v97
	v_cvt_pk_bf16_f32 v74, v165, v186
	v_cvt_pk_bf16_f32 v75, v187, v188
	v_cvt_pk_bf16_f32 v76, v189, v190
	v_cvt_pk_bf16_f32 v77, v191, v192
	s_waitcnt lgkmcnt(7)
	v_mfma_f32_32x32x16_bf16 v[50:65], v[214:217], v[70:73], v[50:65]
	ds_read_b128 v[214:217], v201 offset:44064
	v_exp_f32_e32 v200, v66
	v_cvt_pk_bf16_f32 v66, v193, v194
	v_cvt_pk_bf16_f32 v67, v195, v196
	v_cvt_pk_bf16_f32 v68, v197, v198
	v_cvt_pk_bf16_f32 v69, v199, v200
	v_pk_mul_f32 v[48:49], v[48:49], v[174:175] op_sel_hi:[1,0]
	v_pk_mul_f32 v[46:47], v[46:47], v[174:175] op_sel_hi:[1,0]
	s_waitcnt lgkmcnt(7)
	v_mfma_f32_32x32x16_bf16 v[50:65], v[218:221], v[74:77], v[50:65]
	ds_read_b128 v[218:221], v201 offset:44096
	v_mul_f32_e64 v44, v44, v174
	v_mul_f32_e64 v45, v45, v174
	v_mul_f32_e64 v42, v42, v174
	v_mul_f32_e64 v43, v43, v174
	v_pk_mul_f32 v[40:41], v[40:41], v[174:175] op_sel_hi:[1,0]
	v_pk_mul_f32 v[38:39], v[38:39], v[174:175] op_sel_hi:[1,0]
	v_pk_mul_f32 v[36:37], v[36:37], v[174:175] op_sel_hi:[1,0]
	v_pk_mul_f32 v[34:35], v[34:35], v[174:175] op_sel_hi:[1,0]
	s_waitcnt lgkmcnt(7)
	v_mfma_f32_32x32x16_bf16 v[50:65], v[222:225], v[66:69], v[50:65]
	ds_read_b128 v[222:225], v201 offset:44128
	v_mul_f32_e64 v32, v32, v174
	v_mul_f32_e64 v33, v33, v174
	v_mul_f32_e64 v30, v30, v174
	v_mul_f32_e64 v31, v31, v174
	v_pk_mul_f32 v[28:29], v[28:29], v[174:175] op_sel_hi:[1,0]
	v_pk_mul_f32 v[26:27], v[26:27], v[174:175] op_sel_hi:[1,0]
	v_pk_mul_f32 v[24:25], v[24:25], v[174:175] op_sel_hi:[1,0]
	v_pk_mul_f32 v[22:23], v[22:23], v[174:175] op_sel_hi:[1,0]
	s_waitcnt lgkmcnt(7)
	v_mfma_f32_32x32x16_bf16 v[34:49], v[226:229], v[78:81], v[34:49]
	ds_read_b128 v[226:229], v201 offset:48640
	v_mul_f32_e64 v20, v20, v174
	v_mul_f32_e64 v21, v21, v174
	v_mul_f32_e64 v18, v18, v174
	v_mul_f32_e64 v19, v19, v174
	v_pk_mul_f32 v[16:17], v[16:17], v[174:175] op_sel_hi:[1,0]
	v_pk_mul_f32 v[14:15], v[14:15], v[174:175] op_sel_hi:[1,0]
	v_pk_mul_f32 v[12:13], v[12:13], v[174:175] op_sel_hi:[1,0]
	v_pk_mul_f32 v[10:11], v[10:11], v[174:175] op_sel_hi:[1,0]
	s_waitcnt lgkmcnt(7)
	v_mfma_f32_32x32x16_bf16 v[34:49], v[230:233], v[70:73], v[34:49]
	ds_read_b128 v[230:233], v201 offset:48672
	v_mul_f32_e64 v8, v8, v174
	v_mul_f32_e64 v9, v9, v174
	v_mul_f32_e64 v6, v6, v174
	v_mul_f32_e64 v7, v7, v174
	v_pk_mul_f32 v[4:5], v[4:5], v[174:175] op_sel_hi:[1,0]
	v_pk_mul_f32 v[2:3], v[2:3], v[174:175] op_sel_hi:[1,0]
	s_waitcnt lgkmcnt(7)
	v_mfma_f32_32x32x16_bf16 v[34:49], v[234:237], v[74:77], v[34:49]
	ds_read_b128 v[234:237], v201 offset:48704
	s_waitcnt lgkmcnt(7)
	v_mfma_f32_32x32x16_bf16 v[34:49], v[238:241], v[66:69], v[34:49]
	ds_read_b128 v[238:241], v201 offset:48736
	s_waitcnt lgkmcnt(7)
	v_mfma_f32_32x32x16_bf16 v[18:33], v[204:207], v[78:81], v[18:33]
	s_waitcnt lgkmcnt(6)
	v_mfma_f32_32x32x16_bf16 v[18:33], v[214:217], v[70:73], v[18:33]
	s_waitcnt lgkmcnt(5)
	v_mfma_f32_32x32x16_bf16 v[18:33], v[218:221], v[74:77], v[18:33]
	s_waitcnt lgkmcnt(4)
	v_mfma_f32_32x32x16_bf16 v[18:33], v[222:225], v[66:69], v[18:33]
	s_waitcnt lgkmcnt(3)
	v_mfma_f32_32x32x16_bf16 v[2:17], v[226:229], v[78:81], v[2:17]
	s_waitcnt lgkmcnt(2)
	v_mfma_f32_32x32x16_bf16 v[2:17], v[230:233], v[70:73], v[2:17]
	s_waitcnt lgkmcnt(1)
	v_mfma_f32_32x32x16_bf16 v[2:17], v[234:237], v[74:77], v[2:17]
	s_waitcnt lgkmcnt(0)
	v_mfma_f32_32x32x16_bf16 v[2:17], v[238:241], v[66:69], v[2:17]
	s_cbranch_vccnz .LBB0_1476
	s_xor_b32 s4, s4, 1
	s_mul_i32 s2, s4, 0x4400
	s_add_i32 s5, s2, 0
	s_and_saveexec_b64 s[2:3], s[36:37]
	s_cbranch_execz .LBB0_1473
	v_add3_u32 v66, s5, v176, v177
	s_waitcnt vmcnt(2)
	ds_write_b128 v66, v[130:133]
